# end of in-proj / MLP-in GEMM phases: the drain before the tail kernels waits only for loads and LDS-DMA (vmcnt(32)), the 32 epilogue stores stay in flight under the tail's first loads
# speedup vs baseline: 1.0069x; 1.0069x over previous
; #define G_WAIT_V(n) asm volatile("s_waitcnt vmcnt(" #n ")" ::: "memory")
; #define G_BAR __builtin_amdgcn_s_barrier()
; template <class Epi>
; __device__ __forceinline__ void gemm_phase(LAS unsigned char* lds, const bf16_t* Ag, const bf16_t* Btg, const int K, const int nM, const int nN, const Epi& E) {
;     ...
;     G_WAIT_V(0);
;     if (wr == 0) G_BAR;
;     G_BAR;
.LBB0_84:
	s_waitcnt vmcnt(32)
	s_cmpk_gt_u32 s56, 0xff
	s_cbranch_scc1 .LBB0_86
	s_barrier

; #define G_WAIT_V(n) asm volatile("s_waitcnt vmcnt(" #n ")" ::: "memory")
; #define G_BAR __builtin_amdgcn_s_barrier()
; template <class Epi>
; __device__ __forceinline__ void gemm_phase(LAS unsigned char* lds, const bf16_t* Ag, const bf16_t* Btg, const int K, const int nM, const int nN, const Epi& E) {
;     ...
;     G_WAIT_V(0);
;     if (wr == 0) G_BAR;
;     G_BAR;
.LBB0_878:
	s_waitcnt vmcnt(32)
	s_cmpk_gt_u32 s58, 0xff
	s_cbranch_scc1 .LBB0_880
	s_barrier

; template <class Epi>
; __device__ __forceinline__ void gemm_tail(LAS unsigned char* lds, const bf16_t* Ag, const bf16_t* Btg, const int K, const int N, const Epi& E, const int ufirst, const int ustride) {
;     ...
;     const int nunits = 4 * (N / 64), ks = K / 8, nch = ks / 128, G = ustride;
;     int u = ufirst;
;     bf16x8 af[4], bf[4][4];
;     ...
;     if (u < nunits) T_LOAD(u, 0);
.LBB0_896:
	s_andn2_b64 vcc, exec, s[14:15]
	s_cbranch_vccnz .LBB0_928
	v_readlane_b32 s14, v253, 43
	v_mov_b32_e32 v90, v198
	v_readlane_b32 s15, v253, 44
	s_andn2_b64 vcc, exec, s[14:15]
	v_ashrrev_i32_e32 v91, 6, v90
	v_cndmask_b32_e64 v2, 0, 1, s[14:15]
	v_bfe_u32 v0, v90, 4, 2
	v_cmp_ne_u32_e64 s[44:45], 1, v2
	v_lshlrev_b32_e32 v2, 7, v91
	v_and_b32_e32 v179, 15, v90
	v_lshlrev_b32_e32 v88, 4, v0
	v_ashrrev_i32_e32 v3, 31, v2
	s_cbranch_vccnz .LBB0_899
	v_readlane_b32 s14, v253, 23
	v_lshlrev_b64 v[10:11], 1, v[2:3]
	v_mov_b32_e32 v89, v1
	v_or_b32_e32 v0, s14, v179
	v_lshlrev_b32_e32 v0, 11, v0
	v_lshl_add_u64 v[8:9], s[36:37], 0, v[0:1]
	v_lshl_add_u64 v[8:9], v[8:9], 0, v[10:11]
	v_readlane_b32 s14, v253, 46
	v_lshl_add_u64 v[40:41], v[8:9], 0, v[88:89]
	v_or_b32_e32 v8, s14, v179
	v_ashrrev_i32_e32 v9, 31, v8
	v_lshlrev_b64 v[8:9], 11, v[8:9]
	v_lshl_add_u64 v[8:9], s[6:7], 0, v[8:9]
	v_lshl_add_u64 v[8:9], v[8:9], 0, v[10:11]
	v_lshl_add_u64 v[48:49], v[8:9], 0, v[88:89]
	s_mov_b32 s14, 0x8000
	v_add_co_u32_e32 v60, vcc, s14, v48
	s_mov_b32 s14, 0x18000
	s_nop 0
	v_addc_co_u32_e32 v61, vcc, 0, v49, vcc
	v_add_co_u32_e32 v68, vcc, s33, v48
	s_nop 1
	v_addc_co_u32_e32 v69, vcc, 0, v49, vcc
	v_add_co_u32_e32 v72, vcc, s14, v48
	s_nop 1
	v_addc_co_u32_e32 v73, vcc, 0, v49, vcc
	global_load_dwordx4 v[44:47], v[40:41], off
	global_load_dwordx4 v[52:55], v[40:41], off offset:64
	global_load_dwordx4 v[8:11], v[48:49], off
	global_load_dwordx4 v[16:19], v[48:49], off offset:64
	global_load_dwordx4 v[12:15], v[60:61], off
	global_load_dwordx4 v[24:27], v[60:61], off offset:64
	global_load_dwordx4 v[20:23], v[68:69], off
	global_load_dwordx4 v[32:35], v[68:69], off offset:64
	global_load_dwordx4 v[28:31], v[72:73], off
	global_load_dwordx4 v[36:39], v[72:73], off offset:64
	global_load_dwordx4 v[84:87], v[40:41], off offset:128
	global_load_dwordx4 v[76:79], v[40:41], off offset:192
	s_nop 0
	global_load_dwordx4 v[40:43], v[48:49], off offset:128
	global_load_dwordx4 v[56:59], v[48:49], off offset:192
	s_nop 0
	global_load_dwordx4 v[48:51], v[60:61], off offset:128
	global_load_dwordx4 v[64:67], v[60:61], off offset:192
	s_nop 0
	global_load_dwordx4 v[60:63], v[68:69], off offset:128
	global_load_dwordx4 v[80:83], v[68:69], off offset:192
	s_nop 0
	global_load_dwordx4 v[68:71], v[72:73], off offset:128
	s_nop 0
	global_load_dwordx4 v[72:75], v[72:73], off offset:192
